# v143 + SSD conv wave-uniform fast path: when no lane of the wave has t<3 the four per-tap exec-mask blocks of a unit are skipped (only wait+unpack run); slow path unchanged
# speedup vs baseline: 1.0066x; 1.0031x over previous
.LBB0_158:
	s_mov_b64 s[74:75], 0x1800
	s_min_i32 s32, s46, s42
	s_mul_hi_i32 s47, s32, 0x2aaaaaab
	s_lshr_b32 s50, s47, 31
	s_ashr_i32 s47, s47, 3
	s_add_i32 s47, s47, s50
	s_mul_i32 s50, s47, 0xffffffd0
	s_add_i32 s50, s50, s32
	s_lshl_b32 s47, s47, 6
	s_lshl_b32 s50, s50, 6
	v_or_b32_e32 v228, s50, v56
	v_mov_b32_e32 v229, 0
	v_lshl_add_u64 v[228:229], v[228:229], 1, s[6:7]
	v_add_u32_e32 v232, s47, v57
	v_mad_i64_i32 v[230:231], s[98:99], v232, s67, v[228:229]
	global_load_dwordx4 v[142:145], v[230:231], off
	v_lshl_add_u64 v[230:231], v[230:231], 0, s[74:75]
	global_load_dwordx4 v[146:149], v[230:231], off
	v_lshl_add_u64 v[230:231], v[230:231], 0, s[74:75]
	global_load_dwordx4 v[150:153], v[230:231], off
	v_lshl_add_u64 v[230:231], v[230:231], 0, s[74:75]
	global_load_dwordx4 v[162:165], v[230:231], off
	s_add_i32 s32, s46, s76
	s_min_i32 s32, s32, s42
	s_mul_hi_i32 s47, s32, 0x2aaaaaab
	s_lshr_b32 s50, s47, 31
	s_ashr_i32 s47, s47, 3
	s_add_i32 s47, s47, s50
	s_mul_i32 s50, s47, 0xffffffd0
	s_add_i32 s50, s50, s32
	s_lshl_b32 s47, s47, 6
	s_lshl_b32 s50, s50, 6
	v_or_b32_e32 v228, s50, v56
	v_mov_b32_e32 v229, 0
	v_lshl_add_u64 v[228:229], v[228:229], 1, s[6:7]
	v_add_u32_e32 v232, s47, v57
	v_mad_i64_i32 v[230:231], s[98:99], v232, s67, v[228:229]
	global_load_dwordx4 v[166:169], v[230:231], off
	v_lshl_add_u64 v[230:231], v[230:231], 0, s[74:75]
	global_load_dwordx4 v[170:173], v[230:231], off
	v_lshl_add_u64 v[230:231], v[230:231], 0, s[74:75]
	global_load_dwordx4 v[174:177], v[230:231], off
	v_lshl_add_u64 v[230:231], v[230:231], 0, s[74:75]
	global_load_dwordx4 v[178:181], v[230:231], off
	s_add_i32 s32, s46, s43
	s_min_i32 s32, s32, s42
	s_mul_hi_i32 s47, s32, 0x2aaaaaab
	s_lshr_b32 s50, s47, 31
	s_ashr_i32 s47, s47, 3
	s_add_i32 s47, s47, s50
	s_mul_i32 s50, s47, 0xffffffd0
	s_add_i32 s50, s50, s32
	s_lshl_b32 s47, s47, 6
	s_lshl_b32 s50, s50, 6
	v_or_b32_e32 v228, s50, v56
	v_mov_b32_e32 v229, 0
	v_lshl_add_u64 v[228:229], v[228:229], 1, s[6:7]
	v_add_u32_e32 v232, s47, v57
	v_mad_i64_i32 v[230:231], s[98:99], v232, s67, v[228:229]
	global_load_dwordx4 v[182:185], v[230:231], off
	v_lshl_add_u64 v[230:231], v[230:231], 0, s[74:75]
	global_load_dwordx4 v[186:189], v[230:231], off
	v_lshl_add_u64 v[230:231], v[230:231], 0, s[74:75]
	global_load_dwordx4 v[220:223], v[230:231], off
	v_lshl_add_u64 v[230:231], v[230:231], 0, s[74:75]
	global_load_dwordx4 v[224:227], v[230:231], off
	s_min_i32 s4, s46, s42
	s_mul_hi_i32 s5, s4, 0x2aaaaaab
	s_lshr_b32 s18, s5, 31
	s_ashr_i32 s5, s5, 3
	s_add_i32 s18, s5, s18
	s_mul_i32 s5, s18, 0xffffffd0
	s_lshl_b32 s19, s18, 6
	s_add_i32 s20, s5, s4
	s_add_i32 s4, s19, s92
	s_add_i32 s5, s4, 0xffff8000
	s_lshr_b32 s5, s5, 6
	s_lshl_b32 s22, s20, 6
	s_add_i32 s5, s5, 16
	s_ashr_i32 s21, s4, 11
	s_cmp_lt_i32 s4, 0x8000
	s_cselect_b32 s4, 0x7c0, 0
	s_cselect_b32 s21, s21, s5
	s_and_b32 s4, s4, s19
	s_cmp_gt_i32 s21, 15
	v_or_b32_e32 v52, s22, v56
	v_add_u32_e32 v2, s4, v54
	s_cselect_b64 s[4:5], -1, 0
	s_add_i32 s21, s21, -16
	v_ashrrev_i32_e32 v53, 31, v52
	v_cndmask_b32_e64 v0, 0, 1, s[4:5]
	s_mul_hi_u32 s25, s21, 3
	s_mul_i32 s24, s21, 3
	s_waitcnt lgkmcnt(0)
	v_lshl_add_u64 v[4:5], v[52:53], 2, s[16:17]
	v_cmp_gt_i32_e32 vcc, 3, v2
	v_cmp_ne_u32_e64 s[4:5], 1, v0
	s_cbranch_vccnz .Lssd_slow0
	s_waitcnt vmcnt(11)
	v_lshlrev_b32_e32 v38, 16, v142
	v_and_b32_e32 v106, 0xffff0000, v142
	v_lshlrev_b32_e32 v40, 16, v143
	v_and_b32_e32 v100, 0xffff0000, v143
	v_lshlrev_b32_e32 v103, 16, v144
	v_and_b32_e32 v11, 0xffff0000, v144
	v_lshlrev_b32_e32 v99, 16, v145
	v_and_b32_e32 v13, 0xffff0000, v145
	s_waitcnt vmcnt(10)
	v_lshlrev_b32_e32 v39, 16, v146
	v_and_b32_e32 v107, 0xffff0000, v146
	v_lshlrev_b32_e32 v41, 16, v147
	v_and_b32_e32 v101, 0xffff0000, v147
	v_lshlrev_b32_e32 v102, 16, v148
	v_and_b32_e32 v10, 0xffff0000, v148
	v_lshlrev_b32_e32 v98, 16, v149
	v_and_b32_e32 v12, 0xffff0000, v149
	s_waitcnt vmcnt(9)
	v_lshlrev_b32_e32 v46, 16, v150
	v_and_b32_e32 v112, 0xffff0000, v150
	v_lshlrev_b32_e32 v48, 16, v151
	v_and_b32_e32 v108, 0xffff0000, v151
	v_lshlrev_b32_e32 v111, 16, v152
	v_and_b32_e32 v43, 0xffff0000, v152
	v_lshlrev_b32_e32 v105, 16, v153
	v_and_b32_e32 v45, 0xffff0000, v153
	s_waitcnt vmcnt(8)
	v_lshlrev_b32_e32 v47, 16, v162
	v_and_b32_e32 v113, 0xffff0000, v162
	v_lshlrev_b32_e32 v49, 16, v163
	v_and_b32_e32 v109, 0xffff0000, v163
	v_lshlrev_b32_e32 v110, 16, v164
	v_and_b32_e32 v42, 0xffff0000, v164
	v_lshlrev_b32_e32 v104, 16, v165
	v_and_b32_e32 v44, 0xffff0000, v165
	s_branch .Lssd_join0
.Lssd_slow0:
	s_and_saveexec_b64 s[26:27], vcc
	s_xor_b64 s[26:27], exec, s[26:27]
	s_cbranch_execz .LBB0_161
	s_waitcnt vmcnt(0)
	v_mov_b32_e32 v13, 0
	s_and_b64 vcc, exec, s[4:5]
	v_mov_b32_e32 v99, 0
	v_mov_b32_e32 v11, 0
	v_mov_b32_e32 v103, 0
	v_mov_b32_e32 v100, 0
	v_mov_b32_e32 v40, 0
	v_mov_b32_e32 v106, 0
	v_mov_b32_e32 v38, 0
	s_cbranch_vccnz .LBB0_161
	v_ashrrev_i32_e32 v3, 31, v2
	v_lshl_add_u64 v[6:7], s[24:25], 0, v[2:3]
	v_mad_u64_u32 v[8:9], s[28:29], v6, s86, v[4:5]
	v_mad_i32_i24 v9, v7, s86, v9
	global_load_dwordx4 v[10:13], v[8:9], off offset:16
	global_load_dwordx4 v[38:41], v[8:9], off
	s_waitcnt vmcnt(1)
	v_mov_b32_e32 v99, v12
	v_mov_b32_e32 v103, v10
	s_waitcnt vmcnt(0)
	v_mov_b32_e32 v100, v41
	v_mov_b32_e32 v106, v39

.Lssd_join0:
	s_add_i32 s21, s76, s46
	s_min_i32 s4, s21, s42
	s_mul_hi_i32 s5, s4, 0x2aaaaaab
	s_lshr_b32 s23, s5, 31
	s_ashr_i32 s5, s5, 3
	s_add_i32 s24, s5, s23
	s_mul_i32 s5, s24, 0xffffffd0
	s_lshl_b32 s25, s24, 6
	s_add_i32 s26, s5, s4
	s_add_i32 s4, s25, s92
	s_add_i32 s5, s4, 0xffff8000
	s_lshr_b32 s5, s5, 6
	s_lshl_b32 s28, s26, 6
	s_add_i32 s5, s5, 16
	s_ashr_i32 s23, s4, 11
	s_cmp_lt_i32 s4, 0x8000
	s_cselect_b32 s4, 0x7c0, 0
	s_cselect_b32 s23, s23, s5
	s_and_b32 s4, s4, s25
	s_cmp_gt_i32 s23, 15
	v_or_b32_e32 v50, s28, v56
	v_add_u32_e32 v2, s4, v54
	s_cselect_b64 s[4:5], -1, 0
	s_add_i32 s23, s23, -16
	v_ashrrev_i32_e32 v51, 31, v50
	v_cndmask_b32_e64 v0, 0, 1, s[4:5]
	s_mul_hi_u32 s31, s23, 3
	s_mul_i32 s30, s23, 3
	v_lshl_add_u64 v[4:5], v[50:51], 2, s[16:17]
	v_cmp_gt_i32_e32 vcc, 3, v2
	v_cmp_ne_u32_e64 s[4:5], 1, v0
	s_cbranch_vccnz .Lssd_slow1
	s_waitcnt vmcnt(7)
	v_lshlrev_b32_e32 v34, 16, v166
	v_and_b32_e32 v96, 0xffff0000, v166
	v_lshlrev_b32_e32 v36, 16, v167
	v_and_b32_e32 v92, 0xffff0000, v167
	v_lshlrev_b32_e32 v95, 16, v168
	v_and_b32_e32 v31, 0xffff0000, v168
	v_lshlrev_b32_e32 v91, 16, v169
	v_and_b32_e32 v33, 0xffff0000, v169
	s_waitcnt vmcnt(6)
	v_lshlrev_b32_e32 v35, 16, v170
	v_and_b32_e32 v97, 0xffff0000, v170
	v_lshlrev_b32_e32 v37, 16, v171
	v_and_b32_e32 v93, 0xffff0000, v171
	v_lshlrev_b32_e32 v94, 16, v172
	v_and_b32_e32 v30, 0xffff0000, v172
	v_lshlrev_b32_e32 v90, 16, v173
	v_and_b32_e32 v32, 0xffff0000, v173
	s_waitcnt vmcnt(5)
	v_lshlrev_b32_e32 v26, 16, v174
	v_and_b32_e32 v86, 0xffff0000, v174
	v_lshlrev_b32_e32 v28, 16, v175
	v_and_b32_e32 v84, 0xffff0000, v175
	v_lshlrev_b32_e32 v89, 16, v176
	v_and_b32_e32 v23, 0xffff0000, v176
	v_lshlrev_b32_e32 v83, 16, v177
	v_and_b32_e32 v25, 0xffff0000, v177
	s_waitcnt vmcnt(4)
	v_lshlrev_b32_e32 v27, 16, v178
	v_and_b32_e32 v87, 0xffff0000, v178
	v_lshlrev_b32_e32 v29, 16, v179
	v_and_b32_e32 v85, 0xffff0000, v179
	v_lshlrev_b32_e32 v88, 16, v180
	v_and_b32_e32 v22, 0xffff0000, v180
	v_lshlrev_b32_e32 v82, 16, v181
	v_and_b32_e32 v24, 0xffff0000, v181
	s_branch .Lssd_join1
.Lssd_slow1:
	s_and_saveexec_b64 s[34:35], vcc
	s_xor_b64 s[34:35], exec, s[34:35]
	s_cbranch_execz .LBB0_183
	v_mov_b32_e32 v33, 0
	s_and_b64 vcc, exec, s[4:5]
	v_mov_b32_e32 v91, 0
	v_mov_b32_e32 v31, 0
	v_mov_b32_e32 v95, 0
	v_mov_b32_e32 v92, 0
	v_mov_b32_e32 v36, 0
	v_mov_b32_e32 v96, 0
	v_mov_b32_e32 v34, 0
	s_cbranch_vccnz .LBB0_183
	v_ashrrev_i32_e32 v3, 31, v2
	v_lshl_add_u64 v[6:7], s[30:31], 0, v[2:3]
	v_mad_u64_u32 v[8:9], s[36:37], v6, s86, v[4:5]
	v_mad_i32_i24 v9, v7, s86, v9
	global_load_dwordx4 v[30:33], v[8:9], off offset:16
	global_load_dwordx4 v[34:37], v[8:9], off
	s_waitcnt vmcnt(1)
	v_mov_b32_e32 v91, v32
	v_mov_b32_e32 v95, v30
	s_waitcnt vmcnt(0)
	v_mov_b32_e32 v92, v37
	v_mov_b32_e32 v96, v35

.Lssd_join1:
	s_add_i32 s27, s43, s46
	s_min_i32 s4, s27, s42
	s_mul_hi_i32 s5, s4, 0x2aaaaaab
	s_lshr_b32 s23, s5, 31
	s_ashr_i32 s5, s5, 3
	s_add_i32 s30, s5, s23
	s_mul_i32 s5, s30, 0xffffffd0
	s_lshl_b32 s31, s30, 6
	s_add_i32 s34, s5, s4
	s_add_i32 s4, s31, s92
	s_add_i32 s5, s4, 0xffff8000
	s_lshr_b32 s5, s5, 6
	s_lshl_b32 s36, s34, 6
	s_add_i32 s5, s5, 16
	s_ashr_i32 s23, s4, 11
	s_cmp_lt_i32 s4, 0x8000
	s_cselect_b32 s4, 0x7c0, 0
	s_cselect_b32 s23, s23, s5
	s_and_b32 s4, s4, s31
	s_cmp_gt_i32 s23, 15
	v_or_b32_e32 v76, s36, v56
	v_add_u32_e32 v114, s4, v54
	s_cselect_b64 s[4:5], -1, 0
	s_add_i32 s23, s23, -16
	v_ashrrev_i32_e32 v77, 31, v76
	v_cndmask_b32_e64 v0, 0, 1, s[4:5]
	s_mul_hi_u32 s39, s23, 3
	s_mul_i32 s38, s23, 3
	v_lshl_add_u64 v[116:117], v[76:77], 2, s[16:17]
	v_cmp_gt_i32_e32 vcc, 3, v114
	v_cmp_ne_u32_e64 s[4:5], 1, v0
	s_cbranch_vccnz .Lssd_slow2
	s_waitcnt vmcnt(3)
	v_lshlrev_b32_e32 v18, 16, v182
	v_and_b32_e32 v80, 0xffff0000, v182
	v_lshlrev_b32_e32 v20, 16, v183
	v_and_b32_e32 v74, 0xffff0000, v183
	v_lshlrev_b32_e32 v79, 16, v184
	v_and_b32_e32 v15, 0xffff0000, v184
	v_lshlrev_b32_e32 v73, 16, v185
	v_and_b32_e32 v17, 0xffff0000, v185
	s_waitcnt vmcnt(2)
	v_lshlrev_b32_e32 v19, 16, v186
	v_and_b32_e32 v81, 0xffff0000, v186
	v_lshlrev_b32_e32 v21, 16, v187
	v_and_b32_e32 v75, 0xffff0000, v187
	v_lshlrev_b32_e32 v78, 16, v188
	v_and_b32_e32 v14, 0xffff0000, v188
	v_lshlrev_b32_e32 v72, 16, v189
	v_and_b32_e32 v16, 0xffff0000, v189
	s_waitcnt vmcnt(1)
	v_lshlrev_b32_e32 v6, 16, v220
	v_and_b32_e32 v68, 0xffff0000, v220
	v_lshlrev_b32_e32 v8, 16, v221
	v_and_b32_e32 v64, 0xffff0000, v221
	v_lshlrev_b32_e32 v71, 16, v222
	v_and_b32_e32 v3, 0xffff0000, v222
	v_lshlrev_b32_e32 v67, 16, v223
	v_and_b32_e32 v5, 0xffff0000, v223
	s_waitcnt vmcnt(0)
	v_lshlrev_b32_e32 v7, 16, v224
	v_and_b32_e32 v69, 0xffff0000, v224
	v_lshlrev_b32_e32 v9, 16, v225
	v_and_b32_e32 v65, 0xffff0000, v225
	v_lshlrev_b32_e32 v70, 16, v226
	v_and_b32_e32 v2, 0xffff0000, v226
	v_lshlrev_b32_e32 v66, 16, v227
	v_and_b32_e32 v4, 0xffff0000, v227
	s_branch .Lssd_join2
.Lssd_slow2:
	s_and_saveexec_b64 s[40:41], vcc
	s_xor_b64 s[40:41], exec, s[40:41]
	s_cbranch_execz .LBB0_205
	v_mov_b32_e32 v17, 0
	s_and_b64 vcc, exec, s[4:5]
	v_mov_b32_e32 v73, 0
	v_mov_b32_e32 v15, 0
	v_mov_b32_e32 v79, 0
	v_mov_b32_e32 v74, 0
	v_mov_b32_e32 v20, 0
	v_mov_b32_e32 v80, 0
	v_mov_b32_e32 v18, 0
	s_cbranch_vccnz .LBB0_205
	v_ashrrev_i32_e32 v115, 31, v114
	v_lshl_add_u64 v[2:3], s[38:39], 0, v[114:115]
	v_mad_u64_u32 v[4:5], s[48:49], v2, s86, v[116:117]
	v_mad_i32_i24 v5, v3, s86, v5
	global_load_dwordx4 v[14:17], v[4:5], off offset:16
	global_load_dwordx4 v[18:21], v[4:5], off
	s_waitcnt vmcnt(1)
	v_mov_b32_e32 v73, v16
	v_mov_b32_e32 v79, v14
	s_waitcnt vmcnt(0)
	v_mov_b32_e32 v74, v21
	v_mov_b32_e32 v80, v19

.Lssd_join2:
	v_lshlrev_b64 v[52:53], 2, v[52:53]
	v_add_u32_e32 v233, 0x8000, v52
	ds_read_b128 v[114:117], v233 offset:49168
	ds_read_b128 v[122:125], v233 offset:49152
	ds_read_b128 v[126:129], v233 offset:16
	ds_read_b128 v[130:133], v233
	s_mov_b64 s[38:39], 0x3000
	ds_read_b128 v[134:137], v233 offset:12288
	s_nop 0
	ds_read_b128 v[138:141], v233 offset:12304
	s_movk_i32 s4, 0x6000
	s_mov_b64 s[40:41], 0x6000
	s_mov_b64 s[48:49], 0x9000
	s_mov_b32 s5, 0x9000
	s_cmp_lt_i32 s20, 40
	s_waitcnt lgkmcnt(2)
	v_mov_b32_e32 v118, v130
	s_waitcnt lgkmcnt(1)
	v_mov_b32_e32 v119, v134
	v_pk_mul_f32 v[38:39], v[118:119], v[38:39]
	v_mov_b32_e32 v134, v131
	v_add_f32_e32 v0, v122, v38
	v_add_f32_e32 v0, v0, v39
	s_waitcnt lgkmcnt(0)
	v_mov_b32_e32 v38, v138
	v_mov_b32_e32 v39, v126
	v_mov_b32_e32 v126, v139
	v_pk_mul_f32 v[38:39], v[38:39], v[102:103]
	v_pk_mul_f32 v[10:11], v[126:127], v[10:11]
	v_add_f32_e32 v39, v39, v114
	v_add_f32_e32 v11, v11, v115
	v_add_f32_e32 v118, v38, v39
	v_pk_mul_f32 v[38:39], v[134:135], v[106:107]
	v_add_f32_e32 v107, v10, v11
	v_mov_b32_e32 v10, v132
	v_mov_b32_e32 v11, v136
	v_pk_mul_f32 v[10:11], v[10:11], v[40:41]
	v_mov_b32_e32 v136, v133
	v_add_f32_e32 v10, v124, v10
	v_add_f32_e32 v119, v10, v11
	v_mov_b32_e32 v10, v140
	v_mov_b32_e32 v11, v128
	v_pk_mul_f32 v[10:11], v[10:11], v[98:99]
	v_mov_b32_e32 v128, v141
	v_add_f32_e32 v11, v11, v116
	v_add_f32_e32 v122, v10, v11
	v_pk_mul_f32 v[10:11], v[136:137], v[100:101]
	v_add_f32_e32 v38, v123, v38
	v_add_f32_e32 v10, v125, v10
	v_add_f32_e32 v123, v10, v11
	v_pk_mul_f32 v[10:11], v[128:129], v[12:13]
	v_add_f32_e32 v106, v38, v39
	v_add_f32_e32 v11, v11, v117
	v_add_f32_e32 v124, v10, v11
	s_nop 0
	ds_read_b128 v[10:13], v233 offset:24576
	s_nop 0
	ds_read_b128 v[38:41], v233 offset:24592
	ds_read_b128 v[98:101], v233 offset:36864
	ds_read_b128 v[114:117], v233 offset:36880
	s_waitcnt lgkmcnt(3)
	v_mov_b32_e32 v52, v10
	s_waitcnt lgkmcnt(1)
	v_mov_b32_e32 v53, v98
	v_pk_mul_f32 v[46:47], v[52:53], v[46:47]
	v_mov_b32_e32 v98, v11
	v_add_f32_e32 v0, v0, v46
	v_add_f32_e32 v0, v0, v47
	s_waitcnt lgkmcnt(0)
	v_mov_b32_e32 v46, v114
	v_mov_b32_e32 v47, v38
	v_pk_mul_f32 v[46:47], v[46:47], v[110:111]
	v_mov_b32_e32 v38, v115
	v_add_f32_e32 v10, v47, v118
	v_add_f32_e32 v46, v46, v10
	v_pk_mul_f32 v[10:11], v[98:99], v[112:113]
	s_nop 0
	v_add_f32_e32 v10, v106, v10
	v_add_f32_e32 v47, v10, v11
	v_pk_mul_f32 v[10:11], v[38:39], v[42:43]
	s_nop 0
	v_add_f32_e32 v11, v11, v107
	v_add_f32_e32 v38, v10, v11
	v_mov_b32_e32 v10, v12
	v_mov_b32_e32 v11, v100
	v_pk_mul_f32 v[10:11], v[10:11], v[48:49]
	v_mov_b32_e32 v100, v13
	v_add_f32_e32 v10, v119, v10
	v_add_f32_e32 v12, v10, v11
	v_mov_b32_e32 v10, v116
	v_mov_b32_e32 v11, v40
	v_pk_mul_f32 v[10:11], v[10:11], v[104:105]
	v_mov_b32_e32 v40, v117
	v_add_f32_e32 v11, v11, v122
	v_add_f32_e32 v39, v10, v11
	v_pk_mul_f32 v[10:11], v[100:101], v[108:109]
	s_nop 0
	v_add_f32_e32 v10, v123, v10
	v_add_f32_e32 v13, v10, v11
	v_pk_mul_f32 v[10:11], v[40:41], v[44:45]
	v_mul_f32_e32 v40, 0xbfb8aa3b, v12
	v_exp_f32_e32 v40, v40
	v_mul_f32_e32 v41, 0xbfb8aa3b, v38
	v_exp_f32_e32 v41, v41
	v_add_f32_e32 v11, v11, v124
	v_add_f32_e32 v40, 1.0, v40
	v_rcp_f32_e32 v40, v40
	v_add_f32_e32 v41, 1.0, v41
	v_rcp_f32_e32 v41, v41
	v_add_f32_e32 v10, v10, v11
	v_mul_f32_e32 v11, 0xbfb8aa3b, v0
	v_mul_f32_e32 v12, v12, v40
	v_mul_f32_e32 v40, 0xbfb8aa3b, v13
	v_exp_f32_e32 v11, v11
	v_exp_f32_e32 v40, v40
	v_mul_f32_e32 v38, v38, v41
	v_mul_f32_e32 v41, 0xbfb8aa3b, v39
	v_exp_f32_e32 v41, v41
	v_add_f32_e32 v11, 1.0, v11
	v_add_f32_e32 v40, 1.0, v40
	v_rcp_f32_e32 v11, v11
	v_rcp_f32_e32 v40, v40
	v_add_f32_e32 v41, 1.0, v41
	v_rcp_f32_e32 v41, v41
	v_mul_f32_e32 v0, v0, v11
	v_mul_f32_e32 v11, 0xbfb8aa3b, v47
	v_mul_f32_e32 v13, v13, v40
	v_mul_f32_e32 v40, 0xbfb8aa3b, v46
	v_exp_f32_e32 v11, v11
	v_exp_f32_e32 v40, v40
	v_mul_f32_e32 v39, v39, v41
	v_mul_f32_e32 v41, 0xbfb8aa3b, v10
	v_exp_f32_e32 v41, v41
	v_add_f32_e32 v11, 1.0, v11
	v_add_f32_e32 v40, 1.0, v40
	v_rcp_f32_e32 v11, v11
	v_rcp_f32_e32 v40, v40
	v_add_f32_e32 v41, 1.0, v41
	v_rcp_f32_e32 v41, v41
	v_mul_f32_e32 v11, v47, v11
	v_mul_f32_e32 v40, v46, v40
	v_lshlrev_b64 v[46:47], 2, v[50:51]
	v_add_u32_e32 v233, 0x8000, v46
	v_lshl_add_u64 v[98:99], s[8:9], 0, v[46:47]
	v_mul_f32_e32 v41, v10, v41
	v_cvt_pk_bf16_f32 v10, v0, v11
	v_cvt_pk_bf16_f32 v11, v12, v13
	v_cvt_pk_bf16_f32 v12, v40, v38
	v_cvt_pk_bf16_f32 v13, v39, v41
	ds_read_b128 v[38:41], v233 offset:49168
	s_nop 0
	ds_read_b128 v[42:45], v233 offset:49152
	s_nop 0
	ds_read_b128 v[46:49], v233 offset:16
	ds_read_b128 v[50:53], v233
	ds_read_b128 v[102:105], v233 offset:12288
	s_nop 0
	ds_read_b128 v[106:109], v233 offset:12304
	s_waitcnt lgkmcnt(2)
	v_mov_b32_e32 v100, v50
	s_waitcnt lgkmcnt(1)
	v_mov_b32_e32 v101, v102
	v_pk_mul_f32 v[34:35], v[100:101], v[34:35]
	v_mov_b32_e32 v102, v51
	v_add_f32_e32 v0, v42, v34
	v_add_f32_e32 v100, v0, v35
	s_waitcnt lgkmcnt(0)
	v_mov_b32_e32 v34, v106
	v_mov_b32_e32 v35, v46
	v_pk_mul_f32 v[34:35], v[34:35], v[94:95]
	v_mov_b32_e32 v46, v107
	v_add_f32_e32 v0, v35, v38
	v_add_f32_e32 v94, v34, v0
	v_pk_mul_f32 v[34:35], v[102:103], v[96:97]
	v_pk_mul_f32 v[30:31], v[46:47], v[30:31]
	v_add_f32_e32 v0, v43, v34
	v_add_f32_e32 v51, v0, v35
	v_add_f32_e32 v0, v31, v39
	v_add_f32_e32 v50, v30, v0
	v_mov_b32_e32 v30, v52
	v_mov_b32_e32 v31, v104
	v_pk_mul_f32 v[30:31], v[30:31], v[36:37]
	v_mov_b32_e32 v104, v53
	v_add_f32_e32 v0, v44, v30
	v_add_f32_e32 v0, v0, v31
	v_mov_b32_e32 v30, v108
	v_mov_b32_e32 v31, v48
	v_pk_mul_f32 v[30:31], v[30:31], v[90:91]
	v_mov_b32_e32 v48, v109
	v_add_f32_e32 v31, v31, v40
	v_add_f32_e32 v46, v30, v31
	v_pk_mul_f32 v[30:31], v[104:105], v[92:93]
	v_add_f32_e32 v30, v45, v30
	v_add_f32_e32 v47, v30, v31
	v_pk_mul_f32 v[30:31], v[48:49], v[32:33]
	v_add_f32_e32 v31, v31, v41
	s_nop 0
	v_add_f32_e32 v48, v30, v31
	ds_read_b128 v[34:37], v233 offset:24576
	s_nop 0
	ds_read_b128 v[30:33], v233 offset:24592
	s_nop 0
	ds_read_b128 v[38:41], v233 offset:36864
	s_nop 0
	ds_read_b128 v[42:45], v233 offset:36880
	s_waitcnt lgkmcnt(3)
	v_mov_b32_e32 v52, v34
	s_waitcnt lgkmcnt(1)
	v_mov_b32_e32 v53, v38
	v_pk_mul_f32 v[26:27], v[52:53], v[26:27]
	v_mov_b32_e32 v38, v35
	v_add_f32_e32 v26, v100, v26
	v_add_f32_e32 v34, v26, v27
	s_waitcnt lgkmcnt(0)
	v_mov_b32_e32 v26, v42
	v_mov_b32_e32 v27, v30
	v_pk_mul_f32 v[26:27], v[26:27], v[88:89]
	v_mov_b32_e32 v30, v43
	v_add_f32_e32 v27, v27, v94
	v_add_f32_e32 v42, v26, v27
	v_pk_mul_f32 v[26:27], v[38:39], v[86:87]
	v_pk_mul_f32 v[22:23], v[30:31], v[22:23]
	v_add_f32_e32 v26, v51, v26
	v_add_f32_e32 v23, v23, v50
	v_add_f32_e32 v26, v26, v27
	v_add_f32_e32 v27, v22, v23
	v_mov_b32_e32 v22, v36
	v_mov_b32_e32 v23, v40
	v_pk_mul_f32 v[22:23], v[22:23], v[28:29]
	v_mov_b32_e32 v40, v37
	v_add_f32_e32 v0, v0, v22
	v_add_f32_e32 v0, v0, v23
	v_mov_b32_e32 v22, v44
	v_mov_b32_e32 v23, v32
	v_pk_mul_f32 v[22:23], v[22:23], v[82:83]
	v_mov_b32_e32 v32, v45
	v_add_f32_e32 v23, v23, v46
	v_add_f32_e32 v28, v22, v23
	v_pk_mul_f32 v[22:23], v[40:41], v[84:85]
	s_nop 0
	v_add_f32_e32 v22, v47, v22
	v_add_f32_e32 v29, v22, v23
	v_pk_mul_f32 v[22:23], v[32:33], v[24:25]
	v_mul_f32_e32 v25, 0xbfb8aa3b, v0
	v_exp_f32_e32 v25, v25
	v_mul_f32_e32 v24, 0xbfb8aa3b, v26
	v_exp_f32_e32 v24, v24
	v_add_f32_e32 v23, v23, v48
	v_add_f32_e32 v25, 1.0, v25
	v_rcp_f32_e32 v25, v25
	v_add_f32_e32 v24, 1.0, v24
	v_rcp_f32_e32 v24, v24
	v_add_f32_e32 v22, v22, v23
	v_mul_f32_e32 v0, v0, v25
	v_mul_f32_e32 v25, 0xbfb8aa3b, v29
	v_exp_f32_e32 v25, v25
	v_mul_f32_e32 v24, v26, v24
	v_mul_f32_e32 v26, 0xbfb8aa3b, v42
	v_mul_f32_e32 v23, 0xbfb8aa3b, v34
	v_add_f32_e32 v25, 1.0, v25
	v_rcp_f32_e32 v25, v25
	v_exp_f32_e32 v26, v26
	v_exp_f32_e32 v23, v23
	v_mul_f32_e32 v25, v29, v25
	v_mul_f32_e32 v29, 0xbfb8aa3b, v27
	v_exp_f32_e32 v29, v29
	v_add_f32_e32 v26, 1.0, v26
	v_add_f32_e32 v23, 1.0, v23
	v_rcp_f32_e32 v26, v26
	v_add_f32_e32 v29, 1.0, v29
	v_rcp_f32_e32 v29, v29
	v_rcp_f32_e32 v23, v23
	v_mul_f32_e32 v26, v42, v26
	v_mul_f32_e32 v27, v27, v29
	v_mul_f32_e32 v29, 0xbfb8aa3b, v28
	v_exp_f32_e32 v29, v29
	v_mul_f32_e32 v23, v34, v23
	v_add_f32_e32 v29, 1.0, v29
	v_rcp_f32_e32 v29, v29
	s_nop 0
	v_mul_f32_e32 v28, v28, v29
	v_mul_f32_e32 v29, 0xbfb8aa3b, v22
	v_exp_f32_e32 v29, v29
	s_nop 0
	v_add_f32_e32 v29, 1.0, v29
	v_rcp_f32_e32 v29, v29
	s_nop 0
	v_mul_f32_e32 v29, v22, v29
	v_cvt_pk_bf16_f32 v22, v23, v24
	v_cvt_pk_bf16_f32 v24, v26, v27
	v_lshlrev_b64 v[26:27], 2, v[76:77]
	v_add_u32_e32 v233, 0x8000, v26
	v_cvt_pk_bf16_f32 v23, v0, v25
	v_cvt_pk_bf16_f32 v25, v28, v29
	ds_read_b128 v[28:31], v233 offset:49168
	ds_read_b128 v[40:43], v233 offset:49152
	ds_read_b128 v[44:47], v233 offset:16
	ds_read_b128 v[48:51], v233
	ds_read_b128 v[82:85], v233 offset:12288
	ds_read_b128 v[86:89], v233 offset:12304
	s_waitcnt lgkmcnt(2)
	v_mov_b32_e32 v32, v48
	s_waitcnt lgkmcnt(1)
	v_mov_b32_e32 v33, v82
	v_pk_mul_f32 v[18:19], v[32:33], v[18:19]
	v_mov_b32_e32 v82, v49
	v_add_f32_e32 v0, v40, v18
	v_add_f32_e32 v40, v0, v19
	s_waitcnt lgkmcnt(0)
	v_mov_b32_e32 v18, v86
	v_mov_b32_e32 v19, v44
	v_pk_mul_f32 v[18:19], v[18:19], v[78:79]
	v_mov_b32_e32 v44, v87
	v_add_f32_e32 v0, v19, v28
	v_add_f32_e32 v39, v18, v0
	v_pk_mul_f32 v[18:19], v[82:83], v[80:81]
	v_pk_mul_f32 v[14:15], v[44:45], v[14:15]
	v_add_f32_e32 v0, v41, v18
	v_add_f32_e32 v38, v0, v19
	v_add_f32_e32 v0, v15, v29
	v_add_f32_e32 v37, v14, v0
	v_mov_b32_e32 v14, v50
	v_mov_b32_e32 v15, v84
	v_pk_mul_f32 v[14:15], v[14:15], v[20:21]
	v_mov_b32_e32 v84, v51
	v_add_f32_e32 v0, v42, v14
	v_add_f32_e32 v36, v0, v15
	v_mov_b32_e32 v14, v88
	v_mov_b32_e32 v15, v46
	v_pk_mul_f32 v[14:15], v[14:15], v[72:73]
	v_mov_b32_e32 v46, v89
	v_add_f32_e32 v0, v15, v30
	v_add_f32_e32 v35, v14, v0
	v_pk_mul_f32 v[14:15], v[84:85], v[74:75]
	s_nop 0
	v_add_f32_e32 v0, v43, v14
	v_add_f32_e32 v34, v0, v15
	v_pk_mul_f32 v[14:15], v[46:47], v[16:17]
	v_add_f32_e32 v0, v15, v31
	s_nop 0
	v_add_f32_e32 v0, v14, v0
	ds_read_b128 v[18:21], v233 offset:24576
	s_nop 0
	ds_read_b128 v[14:17], v233 offset:24592
	ds_read_b128 v[26:29], v233 offset:36864
	s_nop 0
	ds_read_b128 v[30:33], v233 offset:36880
	s_barrier
	s_waitcnt lgkmcnt(3)
	v_mov_b32_e32 v42, v18
	s_waitcnt lgkmcnt(1)
	v_mov_b32_e32 v43, v26
	v_pk_mul_f32 v[6:7], v[42:43], v[6:7]
	v_mov_b32_e32 v26, v19
	v_add_f32_e32 v6, v40, v6
	v_add_f32_e32 v18, v6, v7
	s_waitcnt lgkmcnt(0)
	v_mov_b32_e32 v6, v30
	v_mov_b32_e32 v7, v14
	v_pk_mul_f32 v[6:7], v[6:7], v[70:71]
	v_mov_b32_e32 v14, v31
	v_add_f32_e32 v7, v7, v39
	v_add_f32_e32 v30, v6, v7
	v_pk_mul_f32 v[6:7], v[26:27], v[68:69]
	v_pk_mul_f32 v[2:3], v[14:15], v[2:3]
	v_add_f32_e32 v6, v38, v6
	v_add_f32_e32 v3, v3, v37
	v_add_f32_e32 v6, v6, v7
	v_add_f32_e32 v7, v2, v3
	v_mov_b32_e32 v2, v20
	v_mov_b32_e32 v3, v28
	v_pk_mul_f32 v[2:3], v[2:3], v[8:9]
	v_mov_b32_e32 v28, v21
	v_add_f32_e32 v2, v36, v2
	v_add_f32_e32 v8, v2, v3
	v_mov_b32_e32 v2, v32
	v_mov_b32_e32 v3, v16
	v_pk_mul_f32 v[2:3], v[2:3], v[66:67]
	v_mov_b32_e32 v16, v33
	v_add_f32_e32 v3, v3, v35
	v_add_f32_e32 v9, v2, v3
	v_pk_mul_f32 v[2:3], v[28:29], v[64:65]
	s_nop 0
	v_add_f32_e32 v2, v34, v2
	v_add_f32_e32 v14, v2, v3
	v_pk_mul_f32 v[2:3], v[16:17], v[4:5]
	v_mul_f32_e32 v4, 0xbfb8aa3b, v8
	v_exp_f32_e32 v4, v4
	v_add_f32_e32 v0, v3, v0
	v_mul_f32_e32 v3, 0xbfb8aa3b, v6
	v_exp_f32_e32 v3, v3
	v_add_f32_e32 v4, 1.0, v4
	v_rcp_f32_e32 v4, v4
	v_add_f32_e32 v0, v2, v0
	v_add_f32_e32 v3, 1.0, v3
	v_rcp_f32_e32 v3, v3
	v_mul_f32_e32 v4, v8, v4
	v_mul_f32_e32 v8, 0xbfb8aa3b, v7
	v_exp_f32_e32 v8, v8
	v_mul_f32_e32 v2, 0xbfb8aa3b, v18
	v_mul_f32_e32 v3, v6, v3
	v_mul_f32_e32 v6, 0xbfb8aa3b, v30
	v_add_f32_e32 v8, 1.0, v8
	v_rcp_f32_e32 v8, v8
	v_exp_f32_e32 v2, v2
	v_mul_f32_e32 v5, 0xbfb8aa3b, v14
	v_exp_f32_e32 v6, v6
	v_mul_f32_e32 v7, v7, v8
	v_mul_f32_e32 v8, 0xbfb8aa3b, v9
	v_exp_f32_e32 v8, v8
	v_exp_f32_e32 v5, v5
	v_add_f32_e32 v2, 1.0, v2
	v_add_f32_e32 v6, 1.0, v6
	v_add_f32_e32 v8, 1.0, v8
	v_rcp_f32_e32 v8, v8
	v_rcp_f32_e32 v2, v2
	v_add_f32_e32 v5, 1.0, v5
	v_rcp_f32_e32 v6, v6
	v_mul_f32_e32 v8, v9, v8
	v_mul_f32_e32 v9, 0xbfb8aa3b, v0
	v_exp_f32_e32 v9, v9
	v_rcp_f32_e32 v5, v5
	v_mul_f32_e32 v2, v18, v2
	v_mul_f32_e32 v6, v30, v6
	v_add_f32_e32 v9, 1.0, v9
	v_rcp_f32_e32 v9, v9
	v_mul_f32_e32 v5, v14, v5
	v_cvt_pk_bf16_f32 v2, v2, v3
	v_cvt_pk_bf16_f32 v3, v4, v5
	v_mul_f32_e32 v0, v0, v9
	v_cvt_pk_bf16_f32 v4, v6, v7
	v_add_u32_e32 v6, s19, v54
	v_cvt_pk_bf16_f32 v5, v8, v0
	v_ashrrev_i32_e32 v7, 31, v6
	v_lshlrev_b32_e32 v0, 1, v56
	s_cbranch_scc1 .LBB0_226
	v_lshlrev_b64 v[8:9], 10, v[6:7]
	v_lshl_add_u64 v[8:9], s[14:15], 0, v[8:9]
	s_add_i32 s88, s22, 0xfffff600
	v_lshl_add_u64 v[8:9], s[88:89], 1, v[8:9]
	v_lshl_add_u64 v[8:9], v[8:9], 0, v[0:1]
	global_store_dwordx4 v[8:9], v[10:13], off
